# G1/G3/attention-prologue loads de-serialised: all requests first, one wait
# speedup vs baseline: 1.0037x; 1.0037x over previous
; #define LAS __attribute__((address_space(3)))
; #define PRM (*KP())
; DI void gla_load(LAS unsigned char* lds, int l, int b, int h, int c, int off_q  , int off_k, int off_v, int off_pa, int off_wup, int off_bup) {
;     const int tid = TID();
;     const bf16_t* P2 = (const bf16_t*)(LP(PRM.ws) + WS_P2) + ((size_t)b * TPB + (size_t)c * 64) * P2W;
;     { const int row = tid >> 3, c8 = tid & 7;
;       const u32x4 kv = *(const u32x4*)(P2 + (size_t)row * P2W + 256 + h * 64 + c8 * 8); LAS float* kd = (LAS float*)(lds + off_k) + row * 64 + c8 * 8;
;       kd[0] = bf2f(kv.x & 0xffff); kd[1] = bf2f(kv.x >> 16); kd[2] = bf2f(kv.y & 0xffff); kd[3] = bf2f(kv.y >> 16); kd[4] = bf2f(kv.z & 0xffff); kd[5] = bf2f(kv.z >> 16); kd[6] = bf2f(kv.w & 0xffff); kd[7] = bf2f(kv.w >> 16);
;       if (off_q >= 0) { const u32x4 qv = *(const u32x4*)(P2 + (size_t)row * P2W + h * 64 + c8 * 8); LAS float* qd = (LAS float*)(lds + off_q) + row * 64 + c8 * 8;
;         qd[0] = bf2f(qv.x & 0xffff); qd[1] = bf2f(qv.x >> 16); qd[2] = bf2f(qv.y & 0xffff); qd[3] = bf2f(qv.y >> 16); qd[4] = bf2f(qv.z & 0xffff); qd[5] = bf2f(qv.z >> 16); qd[6] = bf2f(qv.w & 0xffff); qd[7] = bf2f(qv.w >> 16); } }
; #pragma unroll
;     for (int i = 0; i < 2; ++i) { const int id = i * 512 + tid, row = id >> 4, c8 = id & 15;
;         const u32x4 vv = *(const u32x4*)(P2 + (size_t)row * P2W + 512 + h * 128 + c8 * 8); LAS float* vd = (LAS float*)(lds + off_v) + row * 128 + c8 * 8;
;         vd[0] = bf2f(vv.x & 0xffff); vd[1] = bf2f(vv.x >> 16); vd[2] = bf2f(vv.y & 0xffff); vd[3] = bf2f(vv.y >> 16); vd[4] = bf2f(vv.z & 0xffff); vd[5] = bf2f(vv.z >> 16); vd[6] = bf2f(vv.w & 0xffff); vd[7] = bf2f(vv.w >> 16); }
;     if (tid < 256) { const int row = tid >> 2, c8 = tid & 3;
;         const u32x4 pv = *(const u32x4*)(P2 + (size_t)row * P2W + 2048 + c8 * 8); LAS float* pd = (LAS float*)(lds + off_pa) + row * 32 + c8 * 8;
;         pd[0] = bf2f(pv.x & 0xffff); pd[1] = bf2f(pv.x >> 16); pd[2] = bf2f(pv.y & 0xffff); pd[3] = bf2f(pv.y >> 16); pd[4] = bf2f(pv.z & 0xffff); pd[5] = bf2f(pv.z >> 16); pd[6] = bf2f(pv.w & 0xffff); pd[7] = bf2f(pv.w >> 16); }
; #pragma unroll
;     for (int i = 0; i < 4; ++i) { const int idx = tid * 4 + i, d = idx >> 10, rr = (idx >> 6) & 15, dk = idx & 63;
;         ((LAS float*)(lds + off_wup))[idx] = PRM.in[I_WUP][((size_t)(l * 2 + d) * 16 + rr) * 256 + h * 64 + dk]; }
.LBB0_339:
	s_mul_hi_i32 s4, s24, 0x3e0f83e1
	s_ashr_i32 s5, s4, 5
	s_lshr_b32 s7, s4, 31
	s_add_i32 s5, s5, s7
	s_mul_i32 s6, s5, 0x84
	s_and_b32 s21, s5, 3
	s_ashr_i32 s25, s4, 7
	v_mov_b32_e32 v16, v222
	v_mov_b32_e32 v0, v222
	s_mov_b64 s[4:5], s[0:1]
	s_sub_i32 s6, s24, s6
	s_load_dwordx2 s[4:5], s[4:5], 0xa8
	s_add_i32 s25, s25, s7
	s_waitcnt lgkmcnt(0)
	s_mul_i32 s12, s6, 0x48000
	s_mul_hi_i32 s11, s6, 0x48000
	s_add_u32 s4, s4, s12
	s_mul_i32 s10, s25, 0x2520000
	s_addc_u32 s5, s5, s11
	s_mul_hi_i32 s7, s25, 0x2520000
	s_add_u32 s4, s4, s10
	s_addc_u32 s5, s5, s7
	s_add_u32 s4, s4, 0x12888000
	s_addc_u32 s5, s5, 0
	v_ashrrev_i32_e32 v6, 3, v0
	s_waitcnt vmcnt(0)
	v_mov_b64_e32 v[10:11], s[4:5]
	v_lshlrev_b32_e32 v1, 3, v0
	s_load_dwordx2 s[12:13], s[0:1], 0x68
	s_load_dwordx2 s[14:15], s[0:1], 0x70
	s_add_u32 s18, s4, 0x1000
	s_addc_u32 s19, s5, 0
	v_mad_i64_i32 v[2:3], s[10:11], v6, s49, v[10:11]
	s_lshl_b32 s40, s21, 7
	v_and_b32_e32 v7, 56, v1
	v_lshl_add_u64 v[2:3], v[2:3], 0, s[40:41]
	v_lshlrev_b32_e32 v176, 1, v7
	v_lshl_add_u64 v[2:3], v[2:3], 0, v[176:177]
	global_load_dwordx4 v[20:23], v[2:3], off offset:512
	v_lshlrev_b32_e32 v6, 8, v6
	v_lshlrev_b32_e32 v7, 2, v7
	v_add3_u32 v12, 0, v6, v7
	s_lshl_b32 s40, s21, 8
	v_ashrrev_i32_e32 v6, 4, v0
	v_and_b32_e32 v4, 0x78, v1
	v_mad_i64_i32 v[2:3], s[10:11], v6, s49, v[10:11]
	v_lshl_add_u64 v[2:3], v[2:3], 0, s[40:41]
	v_lshlrev_b32_e32 v176, 1, v4
	v_lshl_add_u64 v[2:3], v[2:3], 0, v[176:177]
	v_lshl_add_u32 v8, v4, 2, 0
	global_load_dwordx4 v[24:27], v[2:3], off offset:1024
	v_lshl_add_u32 v13, v6, 9, v8
	v_add_u32_e32 v2, 0x200, v0
	v_ashrrev_i32_e32 v6, 4, v2
	v_mad_i64_i32 v[2:3], s[10:11], v6, s49, v[10:11]
	v_lshl_add_u64 v[2:3], v[2:3], 0, s[40:41]
	v_lshl_add_u64 v[2:3], v[2:3], 0, v[176:177]
	global_load_dwordx4 v[28:31], v[2:3], off offset:1024
	v_lshl_add_u32 v14, v6, 9, v8
	v_cmp_gt_i32_e32 vcc, s51, v0
	s_and_saveexec_b64 s[16:17], vcc
	s_cbranch_execz .Lg1_pa_issued
	v_ashrrev_i32_e32 v6, 2, v0
	v_mov_b64_e32 v[2:3], s[18:19]
	v_and_b32_e32 v4, 24, v1
	v_mad_i64_i32 v[2:3], s[10:11], v6, s49, v[2:3]
	v_lshlrev_b32_e32 v176, 1, v4
	v_lshl_add_u64 v[2:3], v[2:3], 0, v[176:177]
	global_load_dwordx4 v[32:35], v[2:3], off
	v_lshlrev_b32_e32 v6, 7, v6
	v_lshlrev_b32_e32 v4, 2, v4
	v_add3_u32 v15, 0, v6, v4
.Lg1_pa_issued:
	s_or_b64 exec, exec, s[16:17]
	v_ashrrev_i32_e32 v2, 8, v0
	v_add_u32_e32 v2, s20, v2
	v_ashrrev_i32_e32 v3, 31, v2
	v_lshlrev_b64 v[2:3], 14, v[2:3]
	v_lshlrev_b32_e32 v6, 6, v0
	v_lshlrev_b32_e32 v17, 4, v0
	s_waitcnt lgkmcnt(0)
	v_lshl_add_u64 v[4:5], s[12:13], 0, v[2:3]
	v_and_b32_e32 v176, 0x3c00, v6
	v_lshl_add_u64 v[4:5], v[4:5], 0, v[176:177]
	v_and_b32_e32 v6, 0xf0, v17
	v_mov_b32_e32 v7, v177
	v_lshl_add_u64 v[4:5], v[4:5], 0, v[6:7]
	v_lshl_add_u64 v[4:5], v[4:5], 0, s[40:41]
	global_load_dwordx4 v[36:39], v[4:5], off
	v_cmp_gt_i32_e32 vcc, s36, v0
	s_and_saveexec_b64 s[16:17], vcc
	s_cbranch_execz .Lg1_bup_issued
	v_ashrrev_i32_e32 v2, 6, v0
	v_add_u32_e32 v2, s20, v2
	v_ashrrev_i32_e32 v3, 31, v2
	v_and_b32_e32 v4, 63, v0
	v_lshlrev_b64 v[2:3], 10, v[2:3]
	v_lshl_add_u64 v[2:3], s[14:15], 0, v[2:3]
	v_lshlrev_b32_e32 v176, 2, v4
	v_lshl_add_u64 v[2:3], v[2:3], 0, v[176:177]
	v_lshl_add_u64 v[2:3], v[2:3], 0, s[40:41]
	global_load_dword v40, v[2:3], off
	v_lshl_add_u32 v18, v0, 2, 0
	v_add_u32_e32 v18, 0x10000, v18
.Lg1_bup_issued:
	s_or_b64 exec, exec, s[16:17]
	s_waitcnt vmcnt(0)
	v_lshlrev_b32_e32 v44, 16, v20
	v_and_b32_e32 v45, 0xffff0000, v20
	v_lshlrev_b32_e32 v46, 16, v21
	v_and_b32_e32 v47, 0xffff0000, v21
	v_lshlrev_b32_e32 v48, 16, v22
	v_and_b32_e32 v49, 0xffff0000, v22
	v_lshlrev_b32_e32 v50, 16, v23
	v_and_b32_e32 v51, 0xffff0000, v23
	ds_write_b128 v12, v[44:47]
	ds_write_b128 v12, v[48:51] offset:16
	v_lshlrev_b32_e32 v44, 16, v24
	v_and_b32_e32 v45, 0xffff0000, v24
	v_lshlrev_b32_e32 v46, 16, v25
	v_and_b32_e32 v47, 0xffff0000, v25
	v_lshlrev_b32_e32 v48, 16, v26
	v_and_b32_e32 v49, 0xffff0000, v26
	v_lshlrev_b32_e32 v50, 16, v27
	v_and_b32_e32 v51, 0xffff0000, v27
	ds_write_b128 v13, v[44:47] offset:16384
	ds_write_b128 v13, v[48:51] offset:16400
	v_lshlrev_b32_e32 v44, 16, v28
	v_and_b32_e32 v45, 0xffff0000, v28
	v_lshlrev_b32_e32 v46, 16, v29
	v_and_b32_e32 v47, 0xffff0000, v29
	v_lshlrev_b32_e32 v48, 16, v30
	v_and_b32_e32 v49, 0xffff0000, v30
	v_lshlrev_b32_e32 v50, 16, v31
	v_and_b32_e32 v51, 0xffff0000, v31
	ds_write_b128 v14, v[44:47] offset:16384
	ds_write_b128 v14, v[48:51] offset:16400
	ds_write_b128 v17, v[36:39] offset:57344
	v_cmp_gt_i32_e32 vcc, s51, v0
	s_and_saveexec_b64 s[16:17], vcc
	s_cbranch_execz .Lg1_pa_stored
	v_lshlrev_b32_e32 v44, 16, v32
	v_and_b32_e32 v45, 0xffff0000, v32
	v_lshlrev_b32_e32 v46, 16, v33
	v_and_b32_e32 v47, 0xffff0000, v33
	v_lshlrev_b32_e32 v48, 16, v34
	v_and_b32_e32 v49, 0xffff0000, v34
	v_lshlrev_b32_e32 v50, 16, v35
	v_and_b32_e32 v51, 0xffff0000, v35
	ds_write_b128 v15, v[44:47] offset:49152
	ds_write_b128 v15, v[48:51] offset:49168
.Lg1_pa_stored:
	s_or_b64 exec, exec, s[16:17]
	v_cmp_gt_i32_e32 vcc, s36, v0
	s_and_saveexec_b64 s[16:17], vcc
	s_cbranch_execz .Lg1_bup_stored
	ds_write_b32 v18, v40
.Lg1_bup_stored:
	s_or_b64 exec, exec, s[16:17]
	s_mov_b64 s[4:5], s[0:1]
	s_waitcnt lgkmcnt(0)
	s_barrier
	s_load_dwordx2 s[10:11], s[4:5], 0xa8
	s_mov_b64 s[4:5], s[0:1]
	s_waitcnt lgkmcnt(0)
	v_and_b32_e32 v17, 63, v16
	s_load_dwordx2 s[12:13], s[4:5], 0xa8
	v_lshlrev_b32_e32 v176, 2, v17
	s_add_i32 s4, 0, 0x10000
	v_ashrrev_i32_e32 v18, 6, v16
	v_add_u32_e32 v21, 0, v176
	v_add_u32_e32 v22, s4, v176
	v_cmp_gt_i32_e32 vcc, 64, v18
	v_add_u32_e32 v19, -8, v18
	v_lshl_or_b32 v20, v18, 8, v176
	s_waitcnt lgkmcnt(0)
	s_and_saveexec_b64 s[14:15], vcc
	s_cbranch_execz .LBB0_346
	ds_read2st64_b32 v[0:1], v21 offset0:224 offset1:225
	ds_read2st64_b32 v[2:3], v21 offset0:226 offset1:227
	ds_read2st64_b32 v[4:5], v21 offset0:228 offset1:229
	ds_read2st64_b32 v[6:7], v21 offset0:230 offset1:231
	ds_read2st64_b32 v[8:9], v21 offset0:232 offset1:233
	ds_read2st64_b32 v[10:11], v21 offset0:234 offset1:235
	ds_read2st64_b32 v[12:13], v21 offset0:236 offset1:237
	ds_read2st64_b32 v[14:15], v21 offset0:238 offset1:239
	ds_read_b32 v23, v22
	v_readlane_b32 s4, v255, 6
	v_add_u32_e32 v24, -8, v18
	s_mov_b64 s[16:17], 0
	v_add_u32_e32 v25, s4, v20
	s_add_i32 s4, 0, 0xc000
	v_lshl_add_u32 v26, v18, 7, s4

; #define LAS __attribute__((address_space(3)))
; DI int TID() { int t = threadIdx.x; asm volatile("" : "+v"(t)); return t; }
; template <bool SHIFT> DI void attn_unit(LAS unsigned char* lds, const bf16_t* Qb, const bf16_t* Kb, const bf16_t* Vt, bf16_t* concat,
;                   int b, int h, int qt, float shift2, float lam, int lam_init_bits, const float* subln_g) {
;     const int tid = TID(), wid = __builtin_amdgcn_readfirstlane(tid >> 6), lane = tid & 63, r = lane & 31, hh = lane >> 5;
;     const size_t rowbase = (size_t)b * TPB;
;     const int q0 = qt * 256;
;     const int nkt = (qt == 0) ? 4 : NCH;
;     const bf16_t* kg = Kb + rowbase * 1024 + h * 128;
;     const bf16_t* vg = Vt + ((size_t)(b * 8 + h) * 128) * TPB;
;     const int krow0 = tid >> 4, kc = tid & 15;
;     const int vrow0 = tid >> 3, vc = tid & 7;
; #pragma unroll
;     for (int i = 0; i < 8; ++i) { const int id = i * 512 + tid, row = id >> 4, c = id & 15;
;         const u32x4 v = *(const u32x4*)(Qb + (rowbase + q0 + row) * 1024 + h * 128 + c * 8);
;         *(LAS u32x4*)(lds + Q_OFF + row * QP + c * 16) = v; }
;     u32x4 sg0, sg1;
;     sg0 = *(const u32x4*)(kg + (size_t)(krow0) * 1024 + kc * 8); sg1 = *(const u32x4*)(kg + (size_t)(krow0 + 32) * 1024 + kc * 8);
;     *(LAS u32x4*)(lds + K_OFF + krow0 * QP + kc * 16) = sg0; *(LAS u32x4*)(lds + K_OFF + (krow0 + 32) * QP + kc * 16) = sg1;
;     sg0 = *(const u32x4*)(vg + (size_t)(vrow0) * TPB + vc * 8); sg1 = *(const u32x4*)(vg + (size_t)(vrow0 + 64) * TPB + vc * 8);
;     *(LAS u32x4*)(lds + V_OFF + vrow0 * VP + vc * 16) = sg0; *(LAS u32x4*)(lds + V_OFF + (vrow0 + 64) * VP + vc * 16) = sg1;
;     if (nkt > 1) { sg0 = *(const u32x4*)(kg + (size_t)(64 + krow0) * 1024 + kc * 8); sg1 = *(const u32x4*)(kg + (size_t)(64 + krow0 + 32) * 1024 + kc * 8); }
;     __syncthreads();
;     f32x16 OT[2][4];
; #pragma unroll
;     for (int m = 0; m < 2; ++m)
; #pragma unroll
;         for (int t = 0; t < 4; ++t)
; #pragma unroll
;             for (int i = 0; i < 16; ++i) OT[m][t][i] = 0.f;
;     float lsum[2] = {0.f, 0.f};
.LBB0_532:
	s_mov_b64 s[4:5], s[0:1]
	s_load_dwordx2 s[20:21], s[4:5], 0xa8
	s_mov_b64 s[4:5], s[0:1]
	s_waitcnt lgkmcnt(0)
	s_load_dwordx2 s[4:5], s[4:5], 0xa8
	s_and_b32 s30, s6, 7
	s_mov_b64 s[6:7], s[0:1]
	s_waitcnt lgkmcnt(0)
	s_load_dwordx2 s[6:7], s[6:7], 0xa8
	s_mov_b64 s[12:13], s[0:1]
	s_waitcnt lgkmcnt(0)
	s_mov_b64 s[14:15], s[0:1]
	s_load_dwordx2 s[12:13], s[12:13], 0xa8
	v_mov_b32_e32 v16, v222
	s_lshl_b32 s18, s22, 3
	s_waitcnt lgkmcnt(0)
	s_load_dwordx2 s[16:17], s[14:15], 0x60
	s_or_b32 s34, s18, s30
	v_readfirstlane_b32 s14, v16
	s_lshl_b32 s37, s23, 8
	s_lshl_b32 s29, s30, 7
	s_ashr_i32 s31, s14, 6
	s_mul_i32 s15, s34, 0x210000
	s_mul_hi_i32 s14, s34, 0x210000
	s_add_u32 s15, s6, s15
	s_addc_u32 s14, s7, s14
	s_add_u32 s18, s15, 0x10788000
	s_mul_i32 s36, s22, 0x2100
	s_addc_u32 s19, s14, 0
	s_mul_hi_i32 s35, s22, 0x2100
	s_add_u32 s14, s36, s37
	s_addc_u32 s15, s35, 0
	s_lshl_b32 s37, s30, 8
	s_add_u32 s20, s20, s37
	v_and_b32_e32 v17, 15, v16
	s_addc_u32 s21, s21, 0
	v_lshlrev_b32_e32 v160, 4, v17
	v_mov_b32_e32 v161, v177
	v_ashrrev_i32_e32 v6, 4, v16
	v_lshl_add_u64 v[0:1], s[20:21], 0, v[160:161]
	s_mov_b64 s[20:21], 0xa488000
	v_ashrrev_i32_e32 v7, 31, v6
	v_lshl_add_u64 v[4:5], v[0:1], 0, s[20:21]
	v_lshl_add_u64 v[0:1], s[14:15], 0, v[6:7]
	v_lshlrev_b64 v[0:1], 11, v[0:1]
	v_lshl_add_u64 v[0:1], v[4:5], 0, v[0:1]
	global_load_dwordx4 v[32:35], v[0:1], off
	s_mov_b64 s[20:21], 0x10000
	v_lshl_add_u64 v[64:65], v[0:1], 0, s[20:21]
	global_load_dwordx4 v[36:39], v[64:65], off
	v_lshl_add_u64 v[64:65], v[64:65], 0, s[20:21]
	global_load_dwordx4 v[40:43], v[64:65], off
	v_lshl_add_u64 v[64:65], v[64:65], 0, s[20:21]
	global_load_dwordx4 v[44:47], v[64:65], off
	v_lshl_add_u64 v[64:65], v[64:65], 0, s[20:21]
	global_load_dwordx4 v[48:51], v[64:65], off
	v_lshl_add_u64 v[64:65], v[64:65], 0, s[20:21]
	global_load_dwordx4 v[52:55], v[64:65], off
	v_lshl_add_u64 v[64:65], v[64:65], 0, s[20:21]
	global_load_dwordx4 v[56:59], v[64:65], off
	v_lshl_add_u64 v[64:65], v[64:65], 0, s[20:21]
	global_load_dwordx4 v[60:63], v[64:65], off
	v_add_u32_e32 v8, 0x200, v16
	v_ashrrev_i32_e32 v8, 4, v8
	v_ashrrev_i32_e32 v9, 31, v8
	v_mul_lo_u32 v210, v6, s54
	v_add_u32_e32 v10, 0, v160
	v_lshl_add_u64 v[12:13], s[14:15], 0, v[8:9]
	v_add_u32_e32 v11, v10, v210
	v_mov_b32_e32 v82, v11
	v_lshlrev_b64 v[12:13], 11, v[12:13]
	v_lshl_add_u64 v[12:13], v[4:5], 0, v[12:13]
	v_add_u32_e32 v9, 0x400, v16
	s_mul_i32 s35, s22, 0x1080000
	s_mul_hi_i32 s30, s22, 0x1080000
	v_ashrrev_i32_e32 v18, 3, v16
	v_add_u32_e32 v19, 64, v18
	v_add3_u32 v20, s47, v210, v160
	v_add_u32_e32 v214, 0x2200, v210
	v_add3_u32 v21, s47, v214, v160
	v_mul_lo_u32 v215, v18, s44
	v_add_u32_e32 v216, 0x2400, v215
	v_bfe_u32 v236, v16, 5, 1
	v_lshlrev_b32_e32 v163, 4, v236
	v_lshlrev_b32_e32 v162, 3, v17
	v_mov_b32_e32 v164, 0
	v_mov_b32_e32 v128, 0
	v_mov_b32_e32 v129, 0
	v_mov_b32_e32 v130, 0
	v_mov_b32_e32 v131, 0
	v_mov_b32_e32 v132, 0
	v_mov_b32_e32 v133, 0
	v_mov_b32_e32 v134, 0
	v_mov_b32_e32 v135, 0
	v_mov_b32_e32 v152, 0
	v_mov_b32_e32 v153, 0
	v_mov_b32_e32 v154, 0
	v_mov_b32_e32 v155, 0
	v_mov_b32_e32 v156, 0
	v_mov_b32_e32 v157, 0
	v_mov_b32_e32 v158, 0
	v_mov_b32_e32 v159, 0
	v_mov_b32_e32 v165, v164
	v_ashrrev_i32_e32 v12, 4, v9
	v_ashrrev_i32_e32 v13, 31, v12
	v_lshl_add_u64 v[14:15], s[14:15], 0, v[12:13]
	v_mad_u64_u32 v[8:9], s[20:21], v8, s54, v[10:11]
	v_lshlrev_b64 v[14:15], 11, v[14:15]
	v_lshl_add_u64 v[14:15], v[4:5], 0, v[14:15]
	v_mad_u64_u32 v[12:13], s[20:21], v12, s54, v[10:11]
	v_add_u32_e32 v8, 0x600, v16
	v_ashrrev_i32_e32 v8, 4, v8
	v_ashrrev_i32_e32 v9, 31, v8
	v_lshl_add_u64 v[14:15], s[14:15], 0, v[8:9]
	v_lshlrev_b64 v[14:15], 11, v[14:15]
	v_lshl_add_u64 v[14:15], v[4:5], 0, v[14:15]
	v_add_u32_e32 v9, 0x800, v16
	v_ashrrev_i32_e32 v12, 4, v9
	v_ashrrev_i32_e32 v13, 31, v12
	v_lshl_add_u64 v[14:15], s[14:15], 0, v[12:13]
	v_mad_u64_u32 v[8:9], s[20:21], v8, s54, v[10:11]
	v_lshlrev_b64 v[14:15], 11, v[14:15]
	v_lshl_add_u64 v[14:15], v[4:5], 0, v[14:15]
	v_mad_u64_u32 v[12:13], s[20:21], v12, s54, v[10:11]
	v_add_u32_e32 v8, 0xa00, v16
	v_ashrrev_i32_e32 v8, 4, v8
	v_ashrrev_i32_e32 v9, 31, v8
	v_lshl_add_u64 v[14:15], s[14:15], 0, v[8:9]
	v_lshlrev_b64 v[14:15], 11, v[14:15]
	v_lshl_add_u64 v[14:15], v[4:5], 0, v[14:15]
	v_add_u32_e32 v9, 0xc00, v16
	v_ashrrev_i32_e32 v12, 4, v9
	v_ashrrev_i32_e32 v13, 31, v12
	v_lshl_add_u64 v[14:15], s[14:15], 0, v[12:13]
	v_mad_u64_u32 v[8:9], s[20:21], v8, s54, v[10:11]
	v_lshlrev_b64 v[14:15], 11, v[14:15]
	v_lshl_add_u64 v[14:15], v[4:5], 0, v[14:15]
	v_mad_u64_u32 v[12:13], s[20:21], v12, s54, v[10:11]
	v_add_u32_e32 v8, 0xe00, v16
	v_ashrrev_i32_e32 v8, 4, v8
	v_ashrrev_i32_e32 v9, 31, v8
	v_lshl_add_u64 v[14:15], s[14:15], 0, v[8:9]
	v_lshlrev_b64 v[14:15], 11, v[14:15]
	v_lshl_add_u64 v[4:5], v[4:5], 0, v[14:15]
	v_mad_u64_u32 v[4:5], s[20:21], v8, s54, v[10:11]
	s_add_u32 s20, s4, s35
	s_addc_u32 s21, s5, s30
	s_add_u32 s20, s20, s37
	v_lshlrev_b64 v[12:13], 11, v[6:7]
	s_addc_u32 s21, s21, 0
	v_lshl_add_u64 v[6:7], s[20:21], 0, v[12:13]
	v_lshl_add_u64 v[8:9], v[6:7], 0, v[160:161]
	s_mov_b32 s20, 0xc588000
	v_add_co_u32_e32 v6, vcc, s20, v8
	s_mov_b32 s20, 0xc598000
	s_nop 0
	v_addc_co_u32_e32 v7, vcc, 0, v9, vcc
	v_add_co_u32_e32 v10, vcc, s20, v8
	s_lshl_b32 s30, s31, 5
	s_nop 0
	v_addc_co_u32_e32 v11, vcc, 0, v9, vcc
	s_cmp_gt_i32 s31, 3
	v_and_b32_e32 v161, 63, v16
	global_load_dwordx4 v[66:69], v[6:7], off
	global_load_dwordx4 v[70:73], v[10:11], off
	v_lshlrev_b32_e32 v10, 4, v16
	v_and_b32_e32 v176, 0x70, v10
	v_mov_b64_e32 v[10:11], s[18:19]
	v_mad_i64_i32 v[14:15], s[18:19], v18, s50, v[10:11]
	v_mad_i64_i32 v[10:11], s[18:19], v19, s50, v[10:11]
	v_lshl_add_u64 v[14:15], v[14:15], 0, v[176:177]
	v_lshl_add_u64 v[10:11], v[10:11], 0, v[176:177]
	s_mov_b32 s18, 0xc5a8000
	v_add3_u32 v19, s43, v216, v176
	global_load_dwordx4 v[74:77], v[14:15], off
	global_load_dwordx4 v[78:81], v[10:11], off
	v_add_co_u32_e32 v10, vcc, s18, v8
	v_add3_u32 v15, s43, v215, v176
	s_nop 0
	v_addc_co_u32_e32 v11, vcc, 0, v9, vcc
	s_mov_b32 s18, 0xc5b8000
	v_add_co_u32_e32 v8, vcc, s18, v8
	v_and_b32_e32 v14, 31, v16
	s_nop 0
	v_addc_co_u32_e32 v9, vcc, 0, v9, vcc
	s_cselect_b64 s[18:19], -1, 0
	s_cmp_lt_i32 s31, 4
	s_cselect_b64 s[20:21], -1, 0
	s_cmp_eq_u32 s23, 0
	s_cselect_b32 s35, 2, 0x82
	s_lshl_b32 s23, s35, 17
	s_or_b32 s36, s23, 0x20000
	v_mul_u32_u24_e32 v237, 0x110, v14
	v_add3_u32 v212, s47, v237, v163
	global_load_dwordx4 v[144:147], v[10:11], off
	global_load_dwordx4 v[148:151], v[8:9], off
	s_waitcnt vmcnt(2)
; #define LAS __attribute__((address_space(3)))
; template <bool SHIFT> DI void attn_unit(LAS unsigned char* lds, const bf16_t* Qb, const bf16_t* Kb, const bf16_t* Vt, bf16_t* concat,
;                   int b, int h, int qt, float shift2, float lam, int lam_init_bits, const float* subln_g) {
;     ...
;         *(LAS u32x4*)(lds + Q_OFF + row * QP + c * 16) = v; }
;     u32x4 sg0, sg1;
;     sg0 = *(const u32x4*)(kg + (size_t)(krow0) * 1024 + kc * 8); sg1 = *(const u32x4*)(kg + (size_t)(krow0 + 32) * 1024 + kc * 8);
;     *(LAS u32x4*)(lds + K_OFF + krow0 * QP + kc * 16) = sg0; *(LAS u32x4*)(lds + K_OFF + (krow0 + 32) * QP + kc * 16) = sg1;
;     sg0 = *(const u32x4*)(vg + (size_t)(vrow0) * TPB + vc * 8); sg1 = *(const u32x4*)(vg + (size_t)(vrow0 + 64) * TPB + vc * 8);
;     *(LAS u32x4*)(lds + V_OFF + vrow0 * VP + vc * 16) = sg0; *(LAS u32x4*)(lds + V_OFF + (vrow0 + 64) * VP + vc * 16) = sg1;
;     if (nkt > 1) { sg0 = *(const u32x4*)(kg + (size_t)(64 + krow0) * 1024 + kc * 8); sg1 = *(const u32x4*)(kg + (size_t)(64 + krow0 + 32) * 1024 + kc * 8); }
;     __syncthreads();
;     f32x16 OT[2][4];
; #pragma unroll
;     for (int m = 0; m < 2; ++m)
; #pragma unroll
;         for (int t = 0; t < 4; ++t)
; #pragma unroll
;             for (int i = 0; i < 16; ++i) OT[m][t][i] = 0.f;
;     float lsum[2] = {0.f, 0.f};
;     const LAS unsigned char* qrow = lds + Q_OFF + (32 * wid + r) * QP + hh * 16;
;     ...
;     const bool lag = wid >= 4;
;     bf16x8 Pc[2][2];
; #pragma unroll
;     for (int m = 0; m < 2; ++m)
; #pragma unroll
;         for (int g = 0; g < 2; ++g) { u32x4 z = {0u, 0u, 0u, 0u}; Pc[m][g] = __builtin_bit_cast(bf16x8, z); }
;     const LAS unsigned char* vold = lds + V_OFF + r * VP + hh * 16;
;     int vcur = 0;
;     for (int kt = 0; kt < nkt; ++kt) {
;         const int cur = kt & 1, nx = cur ^ 1;
;         const int vnx = vcur == 2 ? 0 : vcur + 1;
;         const bool pf = (kt + 1 < nkt);
;         const size_t ko = (size_t)(kt + 1) * 64;
;         if (pf) { *(LAS u32x4*)(lds + K_OFF + nx * K_BYTES + krow0 * QP + kc * 16) = sg0; *(LAS u32x4*)(lds + K_OFF + nx * K_BYTES + (krow0 + 32) * QP + kc * 16) = sg1;
;             sg0 = *(const u32x4*)(vg + (size_t)(vrow0) * TPB + ko + vc * 8); sg1 = *(const u32x4*)(vg + (size_t)(vrow0 + 64) * TPB + ko + vc * 8); }
;         const LAS unsigned char* kb = lds + K_OFF + cur * K_BYTES + r * QP + hh * 16;
	ds_write_b128 v82, v[32:35]
	ds_write_b128 v82, v[36:39] offset:8704
	ds_write_b128 v82, v[40:43] offset:17408
	ds_write_b128 v82, v[44:47] offset:26112
	ds_write_b128 v82, v[48:51] offset:34816
	ds_write_b128 v82, v[52:55] offset:43520
	ds_write_b128 v82, v[56:59] offset:52224
	ds_write_b128 v82, v[60:63] offset:60928
	ds_write_b128 v20, v[66:69]
	ds_write_b128 v21, v[70:73]
	ds_write_b128 v15, v[74:77]
	ds_write_b128 v19, v[78:81]
	v_or_b32_e32 v2, s30, v14
	v_mul_lo_u32 v2, v2, s54
	v_add_u32_e32 v16, 0, v2
	v_mul_u32_u24_e32 v2, 0x90, v14
	v_add3_u32 v213, s43, v2, v163
	v_mov_b32_e32 v2, 0x1080000
	v_mad_i64_i32 v[2:3], s[22:23], s22, v2, v[12:13]
	v_or3_b32 v2, v2, s37, v160
	v_mad_i64_i32 v[0:1], s[72:73], v18, s50, 0
	v_lshl_add_u64 v[166:167], s[4:5], 0, v[2:3]
	v_mov_b32_e32 v2, 0x210000
	v_mad_i64_i32 v[0:1], s[4:5], s34, v2, v[0:1]
	v_or_b32_e32 v0, v0, v176
	v_lshl_add_u64 v[0:1], s[6:7], 0, v[0:1]
	s_mov_b64 s[4:5], 0x10890080
	v_mov_b32_e32 v14, v177
	v_mov_b32_e32 v15, v177
	v_lshl_add_u64 v[168:169], v[0:1], 0, s[4:5]
	v_mov_b32_e32 v0, v177
	v_mov_b32_e32 v1, v177
	v_mov_b32_e32 v2, v177
	v_mov_b32_e32 v3, v177
	v_mov_b32_e32 v4, v177
	v_mov_b32_e32 v5, v177
	v_mov_b32_e32 v6, v177
	v_mov_b32_e32 v7, v177
	v_mov_b32_e32 v8, v177
	v_mov_b32_e32 v9, v177
	v_mov_b32_e32 v10, v177
	v_mov_b32_e32 v11, v177
	v_mov_b32_e32 v12, v177
	v_mov_b32_e32 v13, v177
	v_add_u32_e32 v211, v16, v163
	v_mov_b64_e32 v[62:63], v[14:15]
	v_mov_b64_e32 v[78:79], v[14:15]
	v_mov_b64_e32 v[110:111], v[14:15]
	v_mov_b64_e32 v[30:31], v[14:15]
	v_mov_b64_e32 v[46:47], v[14:15]
	v_mov_b64_e32 v[94:95], v[14:15]
	v_mov_b64_e32 v[126:127], v[14:15]
	s_mov_b64 s[22:23], 0
	v_mov_b64_e32 v[60:61], v[12:13]
	v_mov_b64_e32 v[58:59], v[10:11]
	v_mov_b64_e32 v[56:57], v[8:9]
	v_mov_b64_e32 v[54:55], v[6:7]
	v_mov_b64_e32 v[52:53], v[4:5]
	v_mov_b64_e32 v[50:51], v[2:3]
	v_mov_b64_e32 v[48:49], v[0:1]
	v_mov_b64_e32 v[76:77], v[12:13]
	v_mov_b64_e32 v[74:75], v[10:11]
	v_mov_b64_e32 v[72:73], v[8:9]
	v_mov_b64_e32 v[70:71], v[6:7]
	v_mov_b64_e32 v[68:69], v[4:5]
	v_mov_b64_e32 v[66:67], v[2:3]
	v_mov_b64_e32 v[64:65], v[0:1]
	v_mov_b64_e32 v[108:109], v[12:13]
	v_mov_b64_e32 v[106:107], v[10:11]
	v_mov_b64_e32 v[104:105], v[8:9]
	v_mov_b64_e32 v[102:103], v[6:7]
	v_mov_b64_e32 v[100:101], v[4:5]
	v_mov_b64_e32 v[98:99], v[2:3]
	v_mov_b64_e32 v[96:97], v[0:1]
	v_mov_b64_e32 v[28:29], v[12:13]
	v_mov_b64_e32 v[26:27], v[10:11]
	v_mov_b64_e32 v[24:25], v[8:9]
	v_mov_b64_e32 v[22:23], v[6:7]
	v_mov_b64_e32 v[20:21], v[4:5]
	v_mov_b64_e32 v[18:19], v[2:3]
	v_mov_b64_e32 v[16:17], v[0:1]
	v_mov_b64_e32 v[44:45], v[12:13]
	v_mov_b64_e32 v[42:43], v[10:11]
	v_mov_b64_e32 v[40:41], v[8:9]
	v_mov_b64_e32 v[38:39], v[6:7]
	v_mov_b64_e32 v[36:37], v[4:5]
	v_mov_b64_e32 v[34:35], v[2:3]
	v_mov_b64_e32 v[32:33], v[0:1]
	v_mov_b64_e32 v[92:93], v[12:13]
	v_mov_b64_e32 v[90:91], v[10:11]
	v_mov_b64_e32 v[88:89], v[8:9]
	v_mov_b64_e32 v[86:87], v[6:7]
	v_mov_b64_e32 v[84:85], v[4:5]
	v_mov_b64_e32 v[82:83], v[2:3]
	v_mov_b64_e32 v[80:81], v[0:1]
	v_mov_b64_e32 v[124:125], v[12:13]
	v_mov_b64_e32 v[122:123], v[10:11]
	v_mov_b64_e32 v[120:121], v[8:9]
	v_mov_b64_e32 v[118:119], v[6:7]
	v_mov_b64_e32 v[116:117], v[4:5]
	v_mov_b64_e32 v[114:115], v[2:3]
	v_mov_b64_e32 v[112:113], v[0:1]
	v_mov_b32_e32 v136, v213
	s_mov_b32 s34, 0
	s_waitcnt lgkmcnt(0)
	s_barrier
.LBB0_533:
	s_and_b32 s6, s34, 1
	s_xor_b32 s4, s6, 1
	s_mulk_i32 s4, 0x4400
	s_add_i32 s4, s4, 0
	s_add_i32 s4, s4, 0x11000
	v_add3_u32 v137, s4, v210, v160
	s_waitcnt vmcnt(0)
	ds_write_b128 v137, v[144:147]
	v_add3_u32 v137, s4, v214, v160
	v_add_co_u32_e32 v138, vcc, 0xffef8000, v168
	ds_write_b128 v137, v[148:151]
	s_nop 0
	v_addc_co_u32_e32 v139, vcc, -1, v169, vcc
	global_load_dwordx4 v[144:147], v[138:139], off
	global_load_dwordx4 v[148:151], v[168:169], off
	v_cndmask_b32_e64 v137, 0, 1, s[18:19]
	v_cmp_ne_u32_e64 s[4:5], 1, v137
	s_andn2_b64 vcc, exec, s[18:19]
	s_cbranch_vccnz .LBB0_535
	ds_read_b128 v[138:141], v136
	s_waitcnt lgkmcnt(0)
	v_mfma_f32_32x32x16_bf16 v[112:127], v[138:141], v[156:159], v[112:127]
	v_mfma_f32_32x32x16_bf16 v[96:111], v[138:141], v[132:135], v[96:111]
	ds_read_b128 v[138:141], v136 offset:4608
	s_waitcnt lgkmcnt(0)
	v_mfma_f32_32x32x16_bf16 v[80:95], v[138:141], v[156:159], v[80:95]
	v_mfma_f32_32x32x16_bf16 v[64:79], v[138:141], v[132:135], v[64:79]
	ds_read_b128 v[138:141], v136 offset:9216
	s_waitcnt lgkmcnt(0)
	v_mfma_f32_32x32x16_bf16 v[32:47], v[138:141], v[156:159], v[32:47]
	v_mfma_f32_32x32x16_bf16 v[48:63], v[138:141], v[132:135], v[48:63]
	ds_read_b128 v[138:141], v136 offset:13824
	s_waitcnt lgkmcnt(0)
	v_mfma_f32_32x32x16_bf16 v[16:31], v[138:141], v[156:159], v[16:31]
	v_mfma_f32_32x32x16_bf16 v[0:15], v[138:141], v[132:135], v[0:15]
	ds_read_b128 v[132:135], v136 offset:32
	s_waitcnt lgkmcnt(0)
	v_mfma_f32_32x32x16_bf16 v[112:127], v[132:135], v[152:155], v[112:127]
	v_mfma_f32_32x32x16_bf16 v[96:111], v[132:135], v[128:131], v[96:111]
	ds_read_b128 v[132:135], v136 offset:4640
	s_waitcnt lgkmcnt(0)
	v_mfma_f32_32x32x16_bf16 v[80:95], v[132:135], v[152:155], v[80:95]
	v_mfma_f32_32x32x16_bf16 v[64:79], v[132:135], v[128:131], v[64:79]
	ds_read_b128 v[132:135], v136 offset:9248
	s_waitcnt lgkmcnt(0)
	v_mfma_f32_32x32x16_bf16 v[32:47], v[132:135], v[152:155], v[32:47]
	v_mfma_f32_32x32x16_bf16 v[48:63], v[132:135], v[128:131], v[48:63]
	ds_read_b128 v[132:135], v136 offset:13856
	s_waitcnt lgkmcnt(0)
	v_mfma_f32_32x32x16_bf16 v[16:31], v[132:135], v[152:155], v[16:31]
	v_mfma_f32_32x32x16_bf16 v[0:15], v[132:135], v[128:131], v[0:15]
; #define LAS __attribute__((address_space(3)))
; template <bool SHIFT> DI void attn_unit(LAS unsigned char* lds, const bf16_t* Qb, const bf16_t* Kb, const bf16_t* Vt, bf16_t* concat,
;                   int b, int h, int qt, float shift2, float lam, int lam_init_bits, const float* subln_g) {
;     ...
;     const bool lag = wid >= 4;
;     bf16x8 Pc[2][2];
; #pragma unroll
;     for (int m = 0; m < 2; ++m)
; #pragma unroll
;         for (int g = 0; g < 2; ++g) { u32x4 z = {0u, 0u, 0u, 0u}; Pc[m][g] = __builtin_bit_cast(bf16x8, z); }
;     const LAS unsigned char* vold = lds + V_OFF + r * VP + hh * 16;
;     int vcur = 0;
;     for (int kt = 0; kt < nkt; ++kt) {
;         const int cur = kt & 1, nx = cur ^ 1;
;         const int vnx = vcur == 2 ? 0 : vcur + 1;
;         const bool pf = (kt + 1 < nkt);
;         const size_t ko = (size_t)(kt + 1) * 64;
;         if (pf) { *(LAS u32x4*)(lds + K_OFF + nx * K_BYTES + krow0 * QP + kc * 16) = sg0; *(LAS u32x4*)(lds + K_OFF + nx * K_BYTES + (krow0 + 32) * QP + kc * 16) = sg1;
;             sg0 = *(const u32x4*)(vg + (size_t)(vrow0) * TPB + ko + vc * 8); sg1 = *(const u32x4*)(vg + (size_t)(vrow0 + 64) * TPB + ko + vc * 8); }
;         const LAS unsigned char* kb = lds + K_OFF + cur * K_BYTES + r * QP + hh * 16;
;         const LAS unsigned char* vb = lds + V_OFF + vcur * V_BYTES + r * VP + hh * 16;
; #pragma unroll
;         for (int half = 0; half < 2; ++half) {
;             if (lag) PVH(Pc, vold);
;             QKEXP(Pc, half);
;             if (half == 0 && pf) { *(LAS u32x4*)(lds + V_OFF + vnx * V_BYTES + vrow0 * VP + vc * 16) = sg0; *(LAS u32x4*)(lds + V_OFF + vnx * V_BYTES + (vrow0 + 64) * VP + vc * 16) = sg1;
;                 if (kt + 2 < nkt) { sg0 = *(const u32x4*)(kg + (ko + 64 + krow0) * 1024 + kc * 8); sg1 = *(const u32x4*)(kg + (ko + 64 + krow0 + 32) * 1024 + kc * 8); } }
.LBB0_535:
	s_add_i32 s7, s40, 1
	s_mulk_i32 s6, 0x4400
	s_cmp_lg_u32 s40, 2
	v_add_u32_e32 v190, s6, v212
	ds_read_b128 v[128:131], v211
	ds_read_b128 v[132:135], v190
	s_cselect_b32 s65, s7, 0
	s_mul_i32 s37, s65, 0x4800
	s_add_i32 s6, s37, 0
	s_add_i32 s6, s6, 0x19800
	s_cmp_ge_u32 s34, s35
	s_waitcnt lgkmcnt(0)
	v_mfma_f32_32x32x16_bf16 v[128:143], v[132:135], v[128:131], 0
	ds_read_b128 v[152:155], v190 offset:32
	ds_read_b128 v[156:159], v211 offset:32
	s_waitcnt lgkmcnt(0)
	v_mfma_f32_32x32x16_bf16 v[128:143], v[152:155], v[156:159], v[128:143]
	ds_read_b128 v[152:155], v190 offset:64
	ds_read_b128 v[156:159], v211 offset:64
	s_waitcnt lgkmcnt(0)
	v_mfma_f32_32x32x16_bf16 v[128:143], v[152:155], v[156:159], v[128:143]
	ds_read_b128 v[152:155], v190 offset:96
	ds_read_b128 v[156:159], v211 offset:96
	s_waitcnt lgkmcnt(0)
	v_mfma_f32_32x32x16_bf16 v[128:143], v[152:155], v[156:159], v[128:143]
	s_nop 11
	v_exp_f32_e32 v218, v128
	v_exp_f32_e32 v219, v129
	v_exp_f32_e32 v220, v130
	v_exp_f32_e32 v221, v131
	v_exp_f32_e32 v238, v132
	v_exp_f32_e32 v239, v133
	v_exp_f32_e32 v240, v134
	v_exp_f32_e32 v189, v135
	v_exp_f32_e32 v187, v136
	v_exp_f32_e32 v185, v137
	v_exp_f32_e32 v183, v138
	v_exp_f32_e32 v181, v139
	v_exp_f32_e32 v179, v140
	v_exp_f32_e32 v175, v141
	v_exp_f32_e32 v173, v142
	v_exp_f32_e32 v171, v143
	v_cvt_pk_bf16_f32 v156, v218, v219
	v_cvt_pk_bf16_f32 v157, v220, v221
	v_cvt_pk_bf16_f32 v158, v238, v239
	v_cvt_pk_bf16_f32 v159, v240, v189
	s_nop 1
	v_cvt_pk_bf16_f32 v152, v187, v185
	v_cvt_pk_bf16_f32 v153, v183, v181
	v_cvt_pk_bf16_f32 v154, v179, v175
	v_cvt_pk_bf16_f32 v155, v173, v171
	s_nop 1
	ds_read_b128 v[128:131], v211 offset:128
	ds_read_b128 v[132:135], v190 offset:128
	s_waitcnt lgkmcnt(0)
	v_mfma_f32_32x32x16_bf16 v[128:143], v[132:135], v[128:131], 0
	ds_read_b128 v[192:195], v190 offset:160
	ds_read_b128 v[196:199], v211 offset:160
	s_waitcnt lgkmcnt(0)
	v_mfma_f32_32x32x16_bf16 v[128:143], v[192:195], v[196:199], v[128:143]
	ds_read_b128 v[192:195], v190 offset:192
	ds_read_b128 v[196:199], v211 offset:192
	s_waitcnt lgkmcnt(0)
	v_mfma_f32_32x32x16_bf16 v[128:143], v[192:195], v[196:199], v[128:143]
	ds_read_b128 v[192:195], v190 offset:224
	ds_read_b128 v[196:199], v211 offset:224
	s_waitcnt lgkmcnt(0)
	v_mfma_f32_32x32x16_bf16 v[128:143], v[192:195], v[196:199], v[128:143]
	s_nop 11
	v_exp_f32_e32 v241, v128
	v_exp_f32_e32 v242, v129
	v_exp_f32_e32 v243, v130
	v_exp_f32_e32 v244, v131
	v_exp_f32_e32 v245, v132
	v_exp_f32_e32 v246, v133
	v_exp_f32_e32 v247, v134
	v_exp_f32_e32 v188, v135
	v_exp_f32_e32 v186, v136
	v_exp_f32_e32 v184, v137
	v_exp_f32_e32 v182, v138
	v_exp_f32_e32 v180, v139
	v_exp_f32_e32 v178, v140
	v_exp_f32_e32 v174, v141
	v_exp_f32_e32 v172, v142
	v_exp_f32_e32 v170, v143
	v_add3_u32 v136, s6, v215, v176
	v_cvt_pk_bf16_f32 v132, v241, v242
	v_cvt_pk_bf16_f32 v133, v243, v244
	v_cvt_pk_bf16_f32 v134, v245, v246
	v_cvt_pk_bf16_f32 v135, v247, v188
	s_nop 1
	v_cvt_pk_bf16_f32 v128, v186, v184
	v_cvt_pk_bf16_f32 v129, v182, v180
	v_cvt_pk_bf16_f32 v130, v178, v174
	v_cvt_pk_bf16_f32 v131, v172, v170
	s_nop 1
	s_waitcnt vmcnt(0)
	ds_write_b128 v136, v[144:147]
	v_add3_u32 v136, s6, v216, v176
	ds_write_b128 v136, v[148:151]
	s_cbranch_scc1 .LBB0_537
	v_lshl_add_u64 v[136:137], v[166:167], 0, s[22:23]
	v_add_co_u32_e32 v138, vcc, 0xc5c8000, v136
	s_nop 1
	v_addc_co_u32_e32 v139, vcc, 0, v137, vcc
	v_add_co_u32_e32 v136, vcc, 0xc5d8000, v136
	s_nop 1
	v_addc_co_u32_e32 v137, vcc, 0, v137, vcc
	global_load_dwordx4 v[144:147], v[138:139], off
	global_load_dwordx4 v[148:151], v[136:137], off

; #define LAS __attribute__((address_space(3)))
; DI int TID() { int t = threadIdx.x; asm volatile("" : "+v"(t)); return t; }
; #define PRM (*KP())
; DI void gla_g3_unit(LAS unsigned char* lds, int l, int b, int h, int c) {
;     constexpr int OQ = 0, OK = 16384, OPA = 32768, OWUP = 40960, OBUP = 49152, OG = 50176, OVT = 82944, OQE = 101376, OKE = 110592, OST = 119808, OOT = 0, PB = 144;
;     const int tid = TID(), wid = __builtin_amdgcn_readfirstlane(tid >> 6), lane = tid & 63, r = lane & 31, hh = lane >> 5;
;     const bf16_t* P2 = (const bf16_t*)(LP(PRM.ws) + WS_P2) + ((size_t)b * TPB + (size_t)c * 64) * P2W;
;     {
;         const int row = tid >> 3, c8 = tid & 7;
;         const u32x4 kv = *(const u32x4*)(P2 + (size_t)row * P2W + 256 + h * 64 + c8 * 8); LAS float* kd = (LAS float*)(lds + OK) + row * 64 + c8 * 8;
;         kd[0] = bf2f(kv.x & 0xffff); kd[1] = bf2f(kv.x >> 16); kd[2] = bf2f(kv.y & 0xffff); kd[3] = bf2f(kv.y >> 16); kd[4] = bf2f(kv.z & 0xffff); kd[5] = bf2f(kv.z >> 16); kd[6] = bf2f(kv.w & 0xffff); kd[7] = bf2f(kv.w >> 16);
;         const u32x4 qv = *(const u32x4*)(P2 + (size_t)row * P2W + h * 64 + c8 * 8); LAS float* qd = (LAS float*)(lds + OQ) + row * 64 + c8 * 8;
;         qd[0] = bf2f(qv.x & 0xffff); qd[1] = bf2f(qv.x >> 16); qd[2] = bf2f(qv.y & 0xffff); qd[3] = bf2f(qv.y >> 16); qd[4] = bf2f(qv.z & 0xffff); qd[5] = bf2f(qv.z >> 16); qd[6] = bf2f(qv.w & 0xffff); qd[7] = bf2f(qv.w >> 16);
; #pragma unroll
;         for (int i = 0; i < 2; ++i) { const int id = i * 512 + tid, m = id >> 4, cc = id & 15;
;             const u32x4 vv = *(const u32x4*)(P2 + (size_t)m * P2W + 512 + h * 128 + cc * 8);
;             const int m16 = m & 15, pos = (m & ~15) + 8 * ((m16 >> 2) & 1) + ((m16 >> 3) << 2) + (m16 & 3);
;             LAS unsigned short* vt = (LAS unsigned short*)(lds + OVT + (cc * 8) * PB + pos * 2);
;             vt[0 * (PB / 2)] = vv.x & 0xffff; vt[1 * (PB / 2)] = vv.x >> 16; vt[2 * (PB / 2)] = vv.y & 0xffff; vt[3 * (PB / 2)] = vv.y >> 16;
;             vt[4 * (PB / 2)] = vv.z & 0xffff; vt[5 * (PB / 2)] = vv.z >> 16; vt[6 * (PB / 2)] = vv.w & 0xffff; vt[7 * (PB / 2)] = vv.w >> 16; }
;         if (tid < 256) { const int prow = tid >> 2, p8 = tid & 3;
;             const u32x4 pv = *(const u32x4*)(P2 + (size_t)prow * P2W + 2048 + p8 * 8); LAS float* pd = (LAS float*)(lds + OPA) + prow * 32 + p8 * 8;
.LBB0_618:
	s_andn2_b64 vcc, exec, s[4:5]
	s_cbranch_vccnz .LBB0_611
	s_ashr_i32 s63, s62, 31
	s_mul_i32 s14, s55, 0x2100
	s_lshl_b64 s[12:13], s[62:63], 6
	v_mov_b32_e32 v26, v222
	s_mov_b64 s[4:5], s[0:1]
	s_mul_hi_i32 s15, s55, 0x2100
	s_add_u32 s14, s14, s12
	s_addc_u32 s15, s15, s13
	s_load_dwordx2 s[4:5], s[4:5], 0xa8
	s_mul_i32 s12, s15, 0x1200
	s_mul_hi_u32 s13, s14, 0x1200
	s_waitcnt lgkmcnt(0)
	s_add_i32 s13, s13, s12
	s_mul_i32 s12, s14, 0x1200
	s_add_u32 s4, s4, s12
	s_addc_u32 s5, s5, s13
	s_add_u32 s4, s4, 0x12888000
	s_addc_u32 s5, s5, 0
	v_ashrrev_i32_e32 v27, 3, v26
	v_mov_b64_e32 v[2:3], s[4:5]
	s_lshl_b32 s18, s8, 6
	v_lshlrev_b32_e32 v4, 3, v26
	v_mad_i64_i32 v[0:1], s[12:13], v27, s49, v[2:3]
	s_ashr_i32 s19, s18, 31
	v_and_b32_e32 v5, 56, v4
	v_lshl_add_u64 v[0:1], s[18:19], 1, v[0:1]
	v_lshlrev_b32_e32 v176, 1, v5
	v_lshl_add_u64 v[0:1], v[0:1], 0, v[176:177]
	global_load_dwordx4 v[60:63], v[0:1], off offset:512
	global_load_dwordx4 v[64:67], v[0:1], off
	v_lshlrev_b32_e32 v10, 8, v27
	v_lshlrev_b32_e32 v5, 2, v5
	v_add3_u32 v56, 0, v10, v5
	s_lshl_b32 s12, s8, 7
	v_and_b32_e32 v31, 0x78, v4
	s_ashr_i32 s13, s12, 31
	v_add_u32_e32 v28, 0x200, v26
	v_ashrrev_i32_e32 v29, 6, v26
	v_cmp_gt_i32_e32 vcc, s51, v26
	v_readfirstlane_b32 s28, v29
	v_mov_b32_e32 v0, s48
	v_ashrrev_i32_e32 v8, 4, v26
	v_mad_u32_u24 v5, v31, s44, v0
	v_mad_i64_i32 v[0:1], s[16:17], v8, s49, v[2:3]
	s_lshl_b64 s[16:17], s[12:13], 1
	v_lshlrev_b32_e32 v9, 1, v8
	v_and_b32_e32 v10, 0x7ffffff3, v8
	v_lshl_add_u64 v[6:7], v[0:1], 0, s[16:17]
	v_lshlrev_b32_e32 v0, 1, v31
	v_mov_b32_e32 v1, v177
	v_and_or_b32 v9, v9, 8, v10
	v_lshl_add_u64 v[6:7], v[6:7], 0, v[0:1]
	v_lshlrev_b32_e32 v9, 1, v9
	v_and_b32_e32 v8, 8, v8
	v_add3_u32 v57, v5, v8, v9
	global_load_dwordx4 v[68:71], v[6:7], off offset:1024
	v_ashrrev_i32_e32 v6, 4, v28
	v_mad_i64_i32 v[2:3], s[20:21], v6, s49, v[2:3]
	v_lshl_add_u64 v[2:3], v[2:3], 0, s[16:17]
	v_lshl_add_u64 v[2:3], v[2:3], 0, v[0:1]
	v_lshlrev_b32_e32 v1, 1, v6
	v_and_b32_e32 v7, 0x7ffffff3, v6
	v_and_or_b32 v1, v1, 8, v7
	v_lshlrev_b32_e32 v1, 1, v1
	v_and_b32_e32 v6, 8, v6
	v_add3_u32 v58, v5, v6, v1
	global_load_dwordx4 v[72:75], v[2:3], off offset:1024
	s_and_saveexec_b64 s[20:21], vcc
	s_cbranch_execz .LBB0_621
	v_ashrrev_i32_e32 v1, 2, v26
	v_mov_b64_e32 v[2:3], s[4:5]
	v_and_b32_e32 v5, 24, v4
	v_mad_i64_i32 v[2:3], s[34:35], v1, s49, v[2:3]
	v_lshlrev_b32_e32 v176, 1, v5
	v_lshl_add_u64 v[2:3], v[2:3], 0, v[176:177]
	v_add_co_u32_e32 v2, vcc, 0x1000, v2
	v_lshlrev_b32_e32 v1, 7, v1
	s_nop 0
	v_addc_co_u32_e32 v3, vcc, 0, v3, vcc
	global_load_dwordx4 v[76:79], v[2:3], off
	v_lshlrev_b32_e32 v2, 2, v5
	v_add3_u32 v59, 0, v1, v2
.LBB0_621:
	s_or_b64 exec, exec, s[20:21]
	s_mov_b64 s[20:21], s[0:1]
	s_load_dwordx2 s[20:21], s[20:21], 0x68
	v_ashrrev_i32_e32 v1, 8, v26
	v_add_u32_e32 v2, s27, v1
	v_ashrrev_i32_e32 v3, 31, v2
	v_lshlrev_b64 v[2:3], 14, v[2:3]
	v_lshlrev_b32_e32 v5, 6, v26
	s_waitcnt lgkmcnt(0)
	v_lshl_add_u64 v[6:7], s[20:21], 0, v[2:3]
	v_and_b32_e32 v176, 0x3c00, v5
	v_lshlrev_b32_e32 v1, 4, v26
	v_lshl_add_u64 v[6:7], v[6:7], 0, v[176:177]
	s_lshl_b64 s[20:21], s[18:19], 2
	v_lshl_add_u64 v[6:7], v[6:7], 0, s[20:21]
	v_and_b32_e32 v8, 0xf0, v1
	v_mov_b32_e32 v9, v177
	v_lshl_add_u64 v[6:7], v[6:7], 0, v[8:9]
	global_load_dwordx4 v[80:83], v[6:7], off
	v_add_u32_e32 v85, 0, v1
	v_lshlrev_b32_e32 v10, 2, v26
	v_and_b32_e32 v30, 63, v26
	s_movk_i32 s2, 0x80
	v_cmp_gt_i32_e32 vcc, s2, v26
	v_lshl_add_u32 v52, v26, 2, 0
	v_lshlrev_b32_e32 v8, 2, v30
	s_and_saveexec_b64 s[20:21], vcc
	s_cbranch_execz .LBB0_623
	s_mov_b64 s[34:35], s[0:1]
	s_load_dwordx2 s[34:35], s[34:35], 0x70
	v_add_u32_e32 v2, s27, v29
	v_ashrrev_i32_e32 v3, 31, v2
	v_lshlrev_b64 v[2:3], 10, v[2:3]
	v_mov_b32_e32 v9, v177
	s_waitcnt lgkmcnt(0)
	v_lshl_add_u64 v[2:3], s[34:35], 0, v[2:3]
	v_lshl_add_u64 v[2:3], s[18:19], 2, v[2:3]
	v_lshl_add_u64 v[2:3], v[2:3], 0, v[8:9]
	global_load_dword v84, v[2:3], off
.LBB0_623:
	s_or_b64 exec, exec, s[20:21]
	s_waitcnt vmcnt(0)
	v_lshlrev_b32_e32 v88, 16, v60
	v_and_b32_e32 v89, 0xffff0000, v60
	v_lshlrev_b32_e32 v90, 16, v61
	v_and_b32_e32 v91, 0xffff0000, v61
	v_lshlrev_b32_e32 v92, 16, v62
	v_and_b32_e32 v93, 0xffff0000, v62
	v_lshlrev_b32_e32 v94, 16, v63
	v_and_b32_e32 v95, 0xffff0000, v63
	ds_write_b128 v56, v[88:91] offset:16384
	ds_write_b128 v56, v[92:95] offset:16400
	v_lshlrev_b32_e32 v88, 16, v64
	v_and_b32_e32 v89, 0xffff0000, v64
	v_lshlrev_b32_e32 v90, 16, v65
	v_and_b32_e32 v91, 0xffff0000, v65
	v_lshlrev_b32_e32 v92, 16, v66
	v_and_b32_e32 v93, 0xffff0000, v66
	v_lshlrev_b32_e32 v94, 16, v67
	v_and_b32_e32 v95, 0xffff0000, v67
	ds_write_b128 v56, v[88:91]
	ds_write_b128 v56, v[92:95] offset:16
	ds_write_b16 v57, v68
	ds_write_b16_d16_hi v57, v68 offset:144
	ds_write_b16 v57, v69 offset:288
	ds_write_b16_d16_hi v57, v69 offset:432
	ds_write_b16 v57, v70 offset:576
	ds_write_b16_d16_hi v57, v70 offset:720
	ds_write_b16 v57, v71 offset:864
	ds_write_b16_d16_hi v57, v71 offset:1008
	ds_write_b16 v58, v72
	ds_write_b16_d16_hi v58, v72 offset:144
	ds_write_b16 v58, v73 offset:288
	ds_write_b16_d16_hi v58, v73 offset:432
	ds_write_b16 v58, v74 offset:576
	ds_write_b16_d16_hi v58, v74 offset:720
	ds_write_b16 v58, v75 offset:864
	ds_write_b16_d16_hi v58, v75 offset:1008
	ds_write_b128 v85, v[80:83] offset:40960
	v_cmp_gt_i32_e32 vcc, s51, v26
	s_and_saveexec_b64 s[20:21], vcc
	s_cbranch_execz .Lg3_pa_stored
	v_lshlrev_b32_e32 v88, 16, v76
	v_and_b32_e32 v89, 0xffff0000, v76
	v_lshlrev_b32_e32 v90, 16, v77
	v_and_b32_e32 v91, 0xffff0000, v77
	v_lshlrev_b32_e32 v92, 16, v78
	v_and_b32_e32 v93, 0xffff0000, v78
	v_lshlrev_b32_e32 v94, 16, v79
	v_and_b32_e32 v95, 0xffff0000, v79
	ds_write_b128 v59, v[88:91] offset:32768
	ds_write_b128 v59, v[92:95] offset:32784
.Lg3_pa_stored:
	s_or_b64 exec, exec, s[20:21]
	v_cmp_gt_i32_e32 vcc, s2, v26
	s_and_saveexec_b64 s[20:21], vcc
	s_cbranch_execz .Lg3_bup_stored
	ds_write_b32 v52, v84 offset:49152
